# mix1a dynamic queue alternating poolc (longest window first) and kvstate tiles, on top of the interleaved mix0 queue
# baseline (speedup 1.0000x reference)
.Lmy_m1a_map:
	s_cmpk_lt_i32 s61, 0x800
	s_cbranch_scc0 .LBB0_515
	s_lshr_b32 s71, s61, 1
	s_and_b32 s72, s61, 1
	s_add_i32 s56, s71, 0x400
	s_cmp_lg_u32 s72, 0
	s_cbranch_scc1 .Lmy_m1a_go
	s_lshr_b32 s64, s71, 8
	s_sub_i32 s64, 3, s64
	s_and_b32 s65, s71, 0xff
	s_lshr_b32 s66, s65, 7
	s_and_b32 s67, s65, 0x7e
	s_lshl_b32 s67, s67, 2
	s_and_b32 s68, s65, 1
	s_or_b32 s67, s67, s68
	s_sub_i32 s69, 3, s64
	s_cmp_eq_u32 s66, 0
	s_cselect_b32 s70, s64, s69
	s_lshl_b32 s70, s70, 1
	s_or_b32 s67, s67, s70
	s_lshl_b32 s66, s66, 9
	s_or_b32 s56, s67, s66
